# E63: E62 + two more VALU removed per prompt-FoX tile (sum init folded into first accumulate; rescale threshold m_run+20 kept in a register, updated only on rescale)
# baseline (speedup 1.0000x reference)
.LBB0_1387:
	s_or_b64 exec, exec, s[18:19]
	s_movk_i32 s15, 0x90
	v_mul_lo_u32 v147, v4, s15
	v_lshlrev_b32_e32 v153, 4, v8
	v_add3_u32 v8, 0, v147, v153
	s_waitcnt lgkmcnt(0)
	s_barrier
	s_barrier
	ds_write_b128 v8, v[130:133]
	v_mad_u64_u32 v[8:9], s[16:17], v4, 48, v[8:9]
	v_mul_lo_u32 v174, v6, s15
	v_lshlrev_b32_e32 v175, 4, v5
	ds_write_b128 v8, v[134:137] offset:18432
	v_add3_u32 v8, 0, v174, v175
	v_lshrrev_b32_e32 v2, 2, v2
	s_cmp_lt_i32 s13, s12
	s_movk_i32 s18, 0xc0
	ds_write_b128 v8, v[138:141]
	v_mad_u64_u32 v[8:9], s[16:17], v6, 48, v[8:9]
	v_and_or_b32 v5, v2, 3, v216
	v_and_or_b32 v2, v2, 4, v225
	v_mov_b32_e32 v16, v3
	v_mov_b32_e32 v17, v3
	s_cselect_b64 s[84:85], -1, 0
	s_add_i32 s14, s9, 0x7f
	s_add_i32 s13, s13, s8
	v_mul_lo_u32 v173, v4, s18
	v_mul_lo_u32 v191, v6, s18
	ds_write_b128 v8, v[142:145] offset:18432
	v_lshlrev_b32_e32 v193, 3, v2
	v_mul_u32_u24_e32 v194, 0xc0, v5
	v_add_u32_e32 v196, 0x80, v6
	v_add_u32_e32 v197, 0x80, v4
	v_mov_b32_e32 v2, v3
	v_mov_b32_e32 v4, v3
	v_mov_b32_e32 v5, v3
	v_mov_b32_e32 v6, v3
	v_mov_b32_e32 v7, v3
	v_mov_b32_e32 v8, v3
	v_mov_b32_e32 v9, v3
	v_mov_b32_e32 v10, v3
	v_mov_b32_e32 v11, v3
	v_mov_b32_e32 v12, v3
	v_mov_b32_e32 v13, v3
	v_mov_b32_e32 v14, v3
	v_mov_b32_e32 v15, v3
	v_mov_b64_e32 v[32:33], v[16:17]
	v_mov_b64_e32 v[48:49], v[16:17]
	s_lshr_b32 s14, s14, 7
	s_movk_i32 s72, 0x90
	s_movk_i32 s73, 0xc0
	s_add_i32 s15, s13, 31
	v_add_u32_e32 v195, s13, v188
	s_mov_b32 s16, 0
	v_mov_b32_e32 v158, 0xf149f2ca
	v_mov_b32_e32 v204, 0xf149f2ca
	v_mov_b32_e32 v192, 0
	v_mov_b32_e32 v198, v187
	v_mov_b64_e32 v[30:31], v[14:15]
	v_mov_b64_e32 v[28:29], v[12:13]
	v_mov_b64_e32 v[26:27], v[10:11]
	v_mov_b64_e32 v[24:25], v[8:9]
	v_mov_b64_e32 v[22:23], v[6:7]
	v_mov_b64_e32 v[20:21], v[4:5]
	v_mov_b64_e32 v[18:19], v[2:3]
	v_mov_b64_e32 v[46:47], v[14:15]
	v_mov_b64_e32 v[44:45], v[12:13]
	v_mov_b64_e32 v[42:43], v[10:11]
	v_mov_b64_e32 v[40:41], v[8:9]
	v_mov_b64_e32 v[38:39], v[6:7]
	v_mov_b64_e32 v[36:37], v[4:5]
	v_mov_b64_e32 v[34:35], v[2:3]
	s_mov_b32 s18, 0
	s_waitcnt lgkmcnt(0)
	s_barrier
	v_mov_b32_e32 v4, v197
	v_ashrrev_i32_e32 v5, 31, v4
	v_lshlrev_b64 v[4:5], 9, v[4:5]
	v_lshl_add_u64 v[4:5], v[4:5], 0, v[148:149]
	v_lshlrev_b64 v[4:5], 1, v[4:5]
	v_lshl_add_u64 v[248:249], s[64:65], 0, v[4:5]
	v_lshl_add_u64 v[246:247], s[66:67], 0, v[4:5]
	v_mov_b32_e32 v4, v196
	v_ashrrev_i32_e32 v5, 31, v4
	v_lshlrev_b64 v[4:5], 9, v[4:5]
	v_lshl_add_u64 v[4:5], v[4:5], 0, v[156:157]
	v_lshlrev_b64 v[4:5], 1, v[4:5]
	v_lshl_add_u64 v[250:251], s[64:65], 0, v[4:5]
	v_lshl_add_u64 v[252:253], s[66:67], 0, v[4:5]
	s_mov_b32 s100, 0x20000
	s_mov_b32 s101, 0
	v_add_u32_e32 v200, v147, v153
	v_add_u32_e32 v201, v191, v175
	v_add_u32_e32 v202, v174, v175
	v_add_u32_e32 v203, v173, v153

.LBB0_1393:
	v_max_f32_e32 v4, v50, v51
	v_max3_f32 v2, v82, v83, v84
	v_max3_f32 v4, v4, v52, v53
	v_max3_f32 v2, v2, v85, v86
	v_max3_f32 v4, v4, v54, v55
	v_max3_f32 v2, v2, v87, v88
	v_max3_f32 v4, v4, v56, v57
	v_max3_f32 v2, v2, v89, v90
	v_max3_f32 v4, v4, v58, v59
	v_max3_f32 v2, v2, v91, v92
	v_max3_f32 v4, v4, v60, v61
	v_max3_f32 v2, v2, v93, v94
	v_max3_f32 v4, v4, v62, v63
	v_max3_f32 v2, v2, v95, v96
	v_max3_f32 v4, v4, v64, v65
	v_max3_f32 v2, v2, v97, v4
	v_max_f32_e32 v4, v66, v67
	v_max_f32_e32 v5, v98, v99
	v_max3_f32 v4, v4, v68, v69
	v_max3_f32 v5, v5, v100, v101
	v_max3_f32 v4, v4, v70, v71
	v_max3_f32 v5, v5, v102, v103
	v_max3_f32 v4, v4, v72, v73
	v_max3_f32 v5, v5, v104, v105
	v_max3_f32 v4, v4, v74, v75
	v_max3_f32 v5, v5, v106, v107
	v_max3_f32 v4, v4, v76, v77
	v_max3_f32 v5, v5, v108, v109
	v_max3_f32 v4, v4, v78, v79
	v_max3_f32 v5, v5, v110, v111
	v_max3_f32 v4, v4, v80, v81
	v_max3_f32 v5, v5, v112, v113
	v_max3_f32 v2, v2, v4, v5
	v_mov_b32_e32 v4, v2
	s_nop 1
	v_permlane32_swap_b32_e32 v2, v4
	v_max_f32_e32 v2, v2, v4
	v_cmp_gt_f32_e32 vcc, v2, v204
	s_cbranch_vccz .LBB0_1395
	v_max_f32_e32 v2, v2, v2
	v_max_f32_e32 v4, v158, v158
	v_max_f32_e32 v4, v4, v2
	v_sub_f32_e32 v2, v158, v4
	v_exp_f32_e32 v2, v2
	v_mov_b32_e32 v158, v4
	v_add_f32_e32 v204, 0x41a00000, v158
	v_pk_mul_f32 v[48:49], v[48:49], v[2:3] op_sel_hi:[1,0]
	v_pk_mul_f32 v[46:47], v[46:47], v[2:3] op_sel_hi:[1,0]
	v_pk_mul_f32 v[44:45], v[44:45], v[2:3] op_sel_hi:[1,0]
	v_pk_mul_f32 v[42:43], v[42:43], v[2:3] op_sel_hi:[1,0]
	v_pk_mul_f32 v[40:41], v[40:41], v[2:3] op_sel_hi:[1,0]
	v_pk_mul_f32 v[38:39], v[38:39], v[2:3] op_sel_hi:[1,0]
	v_pk_mul_f32 v[36:37], v[36:37], v[2:3] op_sel_hi:[1,0]
	v_pk_mul_f32 v[34:35], v[34:35], v[2:3] op_sel_hi:[1,0]
	v_pk_mul_f32 v[32:33], v[32:33], v[2:3] op_sel_hi:[1,0]
	v_pk_mul_f32 v[30:31], v[30:31], v[2:3] op_sel_hi:[1,0]
	v_pk_mul_f32 v[28:29], v[28:29], v[2:3] op_sel_hi:[1,0]
	v_pk_mul_f32 v[26:27], v[26:27], v[2:3] op_sel_hi:[1,0]
	v_pk_mul_f32 v[24:25], v[24:25], v[2:3] op_sel_hi:[1,0]
	v_pk_mul_f32 v[22:23], v[22:23], v[2:3] op_sel_hi:[1,0]
	v_pk_mul_f32 v[20:21], v[20:21], v[2:3] op_sel_hi:[1,0]
	v_pk_mul_f32 v[18:19], v[18:19], v[2:3] op_sel_hi:[1,0]
	v_mul_f32_e32 v192, v192, v2
.LBB0_1395:
	v_pk_add_f32 v[10:11], v[86:87], v[158:159] op_sel_hi:[1,0] neg_lo:[0,1] neg_hi:[0,1]
	v_pk_add_f32 v[4:5], v[82:83], v[158:159] op_sel_hi:[1,0] neg_lo:[0,1] neg_hi:[0,1]
	v_exp_f32_e32 v168, v10
	v_exp_f32_e32 v169, v11
	v_pk_add_f32 v[10:11], v[88:89], v[158:159] op_sel_hi:[1,0] neg_lo:[0,1] neg_hi:[0,1]
	v_pk_add_f32 v[6:7], v[84:85], v[158:159] op_sel_hi:[1,0] neg_lo:[0,1] neg_hi:[0,1]
	v_exp_f32_e32 v170, v10
	v_exp_f32_e32 v171, v11
	v_pk_add_f32 v[10:11], v[90:91], v[158:159] op_sel_hi:[1,0] neg_lo:[0,1] neg_hi:[0,1]
	v_exp_f32_e32 v4, v4
	v_exp_f32_e32 v160, v10
	v_exp_f32_e32 v161, v11
	v_pk_add_f32 v[10:11], v[92:93], v[158:159] op_sel_hi:[1,0] neg_lo:[0,1] neg_hi:[0,1]
	v_exp_f32_e32 v5, v5
	v_exp_f32_e32 v162, v10
	v_exp_f32_e32 v163, v11
	v_pk_add_f32 v[10:11], v[94:95], v[158:159] op_sel_hi:[1,0] neg_lo:[0,1] neg_hi:[0,1]
	v_add3_u32 v2, s70, v193, v194
	v_exp_f32_e32 v164, v10
	v_exp_f32_e32 v165, v11
	v_pk_add_f32 v[10:11], v[96:97], v[158:159] op_sel_hi:[1,0] neg_lo:[0,1] neg_hi:[0,1]
	v_exp_f32_e32 v6, v6
	v_exp_f32_e32 v166, v10
	v_exp_f32_e32 v167, v11
	v_pk_add_f32 v[10:11], v[50:51], v[158:159] op_sel_hi:[1,0] neg_lo:[0,1] neg_hi:[0,1]
	v_exp_f32_e32 v7, v7
	v_exp_f32_e32 v90, v10
	v_exp_f32_e32 v91, v11
	v_pk_add_f32 v[10:11], v[52:53], v[158:159] op_sel_hi:[1,0] neg_lo:[0,1] neg_hi:[0,1]
	v_exp_f32_e32 v92, v10
	v_exp_f32_e32 v93, v11
	v_pk_add_f32 v[10:11], v[54:55], v[158:159] op_sel_hi:[1,0] neg_lo:[0,1] neg_hi:[0,1]
	v_pk_add_f32 v[8:9], v[6:7], v[4:5]
	v_exp_f32_e32 v94, v10
	v_exp_f32_e32 v95, v11
	v_pk_add_f32 v[10:11], v[56:57], v[158:159] op_sel_hi:[1,0] neg_lo:[0,1] neg_hi:[0,1]
	v_cvt_pk_bf16_f32 v4, v4, v5
	v_exp_f32_e32 v96, v10
	v_exp_f32_e32 v97, v11
	v_pk_add_f32 v[10:11], v[58:59], v[158:159] op_sel_hi:[1,0] neg_lo:[0,1] neg_hi:[0,1]
	v_cvt_pk_bf16_f32 v5, v6, v7
	v_exp_f32_e32 v82, v10
	v_exp_f32_e32 v83, v11
	v_pk_add_f32 v[10:11], v[60:61], v[158:159] op_sel_hi:[1,0] neg_lo:[0,1] neg_hi:[0,1]
	v_cvt_pk_bf16_f32 v6, v168, v169
	v_exp_f32_e32 v84, v10
	v_exp_f32_e32 v85, v11
	v_pk_add_f32 v[10:11], v[62:63], v[158:159] op_sel_hi:[1,0] neg_lo:[0,1] neg_hi:[0,1]
	v_cvt_pk_bf16_f32 v7, v170, v171
	v_exp_f32_e32 v86, v10
	v_exp_f32_e32 v87, v11
	v_pk_add_f32 v[10:11], v[64:65], v[158:159] op_sel_hi:[1,0] neg_lo:[0,1] neg_hi:[0,1]
	v_pk_add_f32 v[8:9], v[168:169], v[8:9]
	v_exp_f32_e32 v88, v10
	v_exp_f32_e32 v89, v11
	v_pk_add_f32 v[10:11], v[66:67], v[158:159] op_sel_hi:[1,0] neg_lo:[0,1] neg_hi:[0,1]
	v_pk_add_f32 v[8:9], v[170:171], v[8:9]
	v_exp_f32_e32 v66, v10
	v_exp_f32_e32 v67, v11
	v_pk_add_f32 v[10:11], v[68:69], v[158:159] op_sel_hi:[1,0] neg_lo:[0,1] neg_hi:[0,1]
	v_pk_add_f32 v[8:9], v[160:161], v[8:9]
	v_exp_f32_e32 v68, v10
	v_exp_f32_e32 v69, v11
	v_pk_add_f32 v[10:11], v[70:71], v[158:159] op_sel_hi:[1,0] neg_lo:[0,1] neg_hi:[0,1]
	v_pk_add_f32 v[8:9], v[162:163], v[8:9]
	v_exp_f32_e32 v70, v10
	v_exp_f32_e32 v71, v11
	v_pk_add_f32 v[10:11], v[72:73], v[158:159] op_sel_hi:[1,0] neg_lo:[0,1] neg_hi:[0,1]
	v_pk_add_f32 v[8:9], v[164:165], v[8:9]
	v_exp_f32_e32 v72, v10
	v_exp_f32_e32 v73, v11
	v_pk_add_f32 v[10:11], v[74:75], v[158:159] op_sel_hi:[1,0] neg_lo:[0,1] neg_hi:[0,1]
	v_pk_add_f32 v[8:9], v[166:167], v[8:9]
	v_exp_f32_e32 v58, v10
	v_exp_f32_e32 v59, v11
	v_pk_add_f32 v[10:11], v[76:77], v[158:159] op_sel_hi:[1,0] neg_lo:[0,1] neg_hi:[0,1]
	ds_read_b64_tr_b16 v[74:75], v2 offset:18432
	ds_read_b64_tr_b16 v[76:77], v2 offset:19968
	s_waitcnt lgkmcnt(0)
	v_mfma_f32_32x32x16_bf16 v[34:49], v[74:77], v[4:7], v[34:49]
	ds_read_b64_tr_b16 v[74:75], v2 offset:18496
	ds_read_b64_tr_b16 v[76:77], v2 offset:20032
	v_add_f32_e64 v8, v90, v8
	v_add_f32_e64 v9, v91, v9
	v_exp_f32_e32 v60, v10
	v_pk_add_f32 v[8:9], v[92:93], v[8:9]
	v_exp_f32_e32 v61, v11
	v_pk_add_f32 v[8:9], v[94:95], v[8:9]
	v_pk_add_f32 v[10:11], v[78:79], v[158:159] op_sel_hi:[1,0] neg_lo:[0,1] neg_hi:[0,1]
	s_waitcnt lgkmcnt(0)
	v_mfma_f32_32x32x16_bf16 v[18:33], v[74:77], v[4:7], v[18:33]
	ds_read_b64_tr_b16 v[74:75], v2 offset:21504
	ds_read_b64_tr_b16 v[76:77], v2 offset:23040
	v_cvt_pk_bf16_f32 v4, v160, v161
	v_cvt_pk_bf16_f32 v5, v162, v163
	v_cvt_pk_bf16_f32 v6, v164, v165
	v_cvt_pk_bf16_f32 v7, v166, v167
	v_pk_add_f32 v[8:9], v[96:97], v[8:9]
	v_exp_f32_e32 v62, v10
	s_waitcnt lgkmcnt(0)
	v_mfma_f32_32x32x16_bf16 v[34:49], v[74:77], v[4:7], v[34:49]
	ds_read_b64_tr_b16 v[74:75], v2 offset:21568
	ds_read_b64_tr_b16 v[76:77], v2 offset:23104
	v_add_f32_e64 v8, v82, v8
	v_add_f32_e64 v9, v83, v9
	v_exp_f32_e32 v63, v11
	v_pk_add_f32 v[8:9], v[84:85], v[8:9]
	v_pk_add_f32 v[10:11], v[80:81], v[158:159] op_sel_hi:[1,0] neg_lo:[0,1] neg_hi:[0,1]
	v_pk_add_f32 v[8:9], v[86:87], v[8:9]
	v_exp_f32_e32 v64, v10
	s_waitcnt lgkmcnt(0)
	v_mfma_f32_32x32x16_bf16 v[18:33], v[74:77], v[4:7], v[18:33]
	ds_read_b64_tr_b16 v[74:75], v2 offset:24576
	ds_read_b64_tr_b16 v[76:77], v2 offset:26112
	v_cvt_pk_bf16_f32 v4, v90, v91
	v_cvt_pk_bf16_f32 v5, v92, v93
	v_cvt_pk_bf16_f32 v6, v94, v95
	v_cvt_pk_bf16_f32 v7, v96, v97
	v_pk_add_f32 v[8:9], v[88:89], v[8:9]
	v_exp_f32_e32 v65, v11
	s_waitcnt lgkmcnt(0)
	v_mfma_f32_32x32x16_bf16 v[34:49], v[74:77], v[4:7], v[34:49]
	ds_read_b64_tr_b16 v[74:75], v2 offset:24640
	ds_read_b64_tr_b16 v[76:77], v2 offset:26176
	v_add_f32_e64 v8, v66, v8
	v_add_f32_e64 v9, v67, v9
	v_add_f32_e64 v10, v98, -v158
	v_add_f32_e64 v11, v99, -v158
	v_pk_add_f32 v[8:9], v[68:69], v[8:9]
	v_exp_f32_e32 v50, v10
	v_pk_add_f32 v[8:9], v[70:71], v[8:9]
	v_exp_f32_e32 v51, v11
	s_waitcnt lgkmcnt(0)
	v_mfma_f32_32x32x16_bf16 v[18:33], v[74:77], v[4:7], v[18:33]
	ds_read_b64_tr_b16 v[74:75], v2 offset:27648
	ds_read_b64_tr_b16 v[76:77], v2 offset:29184
	v_cvt_pk_bf16_f32 v4, v82, v83
	v_cvt_pk_bf16_f32 v5, v84, v85
	v_cvt_pk_bf16_f32 v6, v86, v87
	v_cvt_pk_bf16_f32 v7, v88, v89
	v_pk_add_f32 v[8:9], v[72:73], v[8:9]
	v_pk_add_f32 v[10:11], v[100:101], v[158:159] op_sel_hi:[1,0] neg_lo:[0,1] neg_hi:[0,1]
	s_waitcnt lgkmcnt(0)
	v_mfma_f32_32x32x16_bf16 v[34:49], v[74:77], v[4:7], v[34:49]
	ds_read_b64_tr_b16 v[74:75], v2 offset:27712
	ds_read_b64_tr_b16 v[76:77], v2 offset:29248
	v_add_f32_e64 v8, v58, v8
	v_add_f32_e64 v9, v59, v9
	v_exp_f32_e32 v52, v10
	v_pk_add_f32 v[8:9], v[60:61], v[8:9]
	v_exp_f32_e32 v53, v11
	v_pk_add_f32 v[8:9], v[62:63], v[8:9]
	v_pk_add_f32 v[10:11], v[102:103], v[158:159] op_sel_hi:[1,0] neg_lo:[0,1] neg_hi:[0,1]
	s_waitcnt lgkmcnt(0)
	v_mfma_f32_32x32x16_bf16 v[18:33], v[74:77], v[4:7], v[18:33]
	v_cvt_pk_bf16_f32 v4, v66, v67
	v_cvt_pk_bf16_f32 v5, v68, v69
	ds_read_b64_tr_b16 v[66:67], v2 offset:30720
	ds_read_b64_tr_b16 v[68:69], v2 offset:32256
	v_cvt_pk_bf16_f32 v6, v70, v71
	v_cvt_pk_bf16_f32 v7, v72, v73
	v_pk_add_f32 v[8:9], v[64:65], v[8:9]
	v_exp_f32_e32 v54, v10
	s_waitcnt lgkmcnt(0)
	v_mfma_f32_32x32x16_bf16 v[34:49], v[66:69], v[4:7], v[34:49]
	ds_read_b64_tr_b16 v[66:67], v2 offset:30784
	ds_read_b64_tr_b16 v[68:69], v2 offset:32320
	v_add_f32_e64 v8, v50, v8
	v_add_f32_e64 v9, v51, v9
	v_exp_f32_e32 v55, v11
	v_pk_add_f32 v[10:11], v[104:105], v[158:159] op_sel_hi:[1,0] neg_lo:[0,1] neg_hi:[0,1]
	v_pk_add_f32 v[8:9], v[52:53], v[8:9]
	v_exp_f32_e32 v56, v10
	v_exp_f32_e32 v57, v11
	s_waitcnt lgkmcnt(0)
	v_mfma_f32_32x32x16_bf16 v[18:33], v[66:69], v[4:7], v[18:33]
	v_cvt_pk_bf16_f32 v4, v58, v59
	v_cvt_pk_bf16_f32 v5, v60, v61
	ds_read_b64_tr_b16 v[58:59], v2 offset:33792
	ds_read_b64_tr_b16 v[60:61], v2 offset:35328
	v_cvt_pk_bf16_f32 v6, v62, v63
	v_cvt_pk_bf16_f32 v7, v64, v65
	v_pk_add_f32 v[10:11], v[106:107], v[158:159] op_sel_hi:[1,0] neg_lo:[0,1] neg_hi:[0,1]
	v_pk_add_f32 v[12:13], v[108:109], v[158:159] op_sel_hi:[1,0] neg_lo:[0,1] neg_hi:[0,1]
	s_waitcnt lgkmcnt(0)
	v_mfma_f32_32x32x16_bf16 v[34:49], v[58:61], v[4:7], v[34:49]
	ds_read_b64_tr_b16 v[58:59], v2 offset:33856
	ds_read_b64_tr_b16 v[60:61], v2 offset:35392
	v_exp_f32_e32 v10, v10
	v_exp_f32_e32 v11, v11
	v_exp_f32_e32 v12, v12
	v_exp_f32_e32 v13, v13
	v_pk_add_f32 v[8:9], v[54:55], v[8:9]
	v_pk_add_f32 v[14:15], v[110:111], v[158:159] op_sel_hi:[1,0] neg_lo:[0,1] neg_hi:[0,1]
	s_waitcnt lgkmcnt(0)
	v_mfma_f32_32x32x16_bf16 v[18:33], v[58:61], v[4:7], v[18:33]
	v_cvt_pk_bf16_f32 v4, v50, v51
	v_cvt_pk_bf16_f32 v5, v52, v53
	ds_read_b64_tr_b16 v[50:51], v2 offset:36864
	ds_read_b64_tr_b16 v[52:53], v2 offset:38400
	v_cvt_pk_bf16_f32 v6, v54, v55
	v_cvt_pk_bf16_f32 v7, v56, v57
	v_pk_add_f32 v[8:9], v[56:57], v[8:9]
	v_pk_add_f32 v[16:17], v[112:113], v[158:159] op_sel_hi:[1,0] neg_lo:[0,1] neg_hi:[0,1]
	s_waitcnt lgkmcnt(0)
	v_mfma_f32_32x32x16_bf16 v[34:49], v[50:53], v[4:7], v[34:49]
	ds_read_b64_tr_b16 v[50:51], v2 offset:36928
	ds_read_b64_tr_b16 v[52:53], v2 offset:38464
	v_add_f32_e64 v8, v10, v8
	v_add_f32_e64 v9, v11, v9
	v_exp_f32_e32 v14, v14
	v_pk_add_f32 v[8:9], v[12:13], v[8:9]
	v_exp_f32_e32 v15, v15
	v_exp_f32_e32 v16, v16
	v_exp_f32_e32 v17, v17
	s_waitcnt lgkmcnt(0)
	v_mfma_f32_32x32x16_bf16 v[18:33], v[50:53], v[4:7], v[18:33]
	v_cvt_pk_bf16_f32 v4, v10, v11
	v_cvt_pk_bf16_f32 v5, v12, v13
	ds_read_b64_tr_b16 v[10:11], v2 offset:39936
	ds_read_b64_tr_b16 v[12:13], v2 offset:41472
	v_cvt_pk_bf16_f32 v6, v14, v15
	v_cvt_pk_bf16_f32 v7, v16, v17
	v_pk_add_f32 v[8:9], v[14:15], v[8:9]
	s_waitcnt lgkmcnt(0)
	v_mfma_f32_32x32x16_bf16 v[34:49], v[10:13], v[4:7], v[34:49]
	ds_read_b64_tr_b16 v[10:11], v2 offset:40000
	ds_read_b64_tr_b16 v[12:13], v2 offset:41536
	v_add_f32_e64 v8, v16, v8
	v_add_f32_e64 v9, v17, v9
	v_add_f32_e32 v2, v8, v9
	v_add_f32_e32 v192, v192, v2
	s_waitcnt lgkmcnt(0)
	v_mfma_f32_32x32x16_bf16 v[18:33], v[10:13], v[4:7], v[18:33]
